# FFN-in K-loop with 3 barrier intervals per K-tile (even K-tile as one 64-MFMA segment with mid-segment As1 reads, odd K-tile as two 32-MFMA segments), per-half LDS-DMA placement keeps every load group
# speedup vs baseline: 1.0037x; 1.0037x over previous
; #define PG8_STAGE(bufoff, gbase, voff) do { _Pragma("unroll") for (int _i = 0; _i < 2; ++_i) \
;         __builtin_amdgcn_global_load_lds((const unsigned*)((const char*)(gbase) + (voff)[_i]), (PG8_LAS unsigned*)(lds + (bufoff) + ldsw + _i * 8192), 16, 0, 0); } while (0)
; #define PG8_WAIT_V(n) asm volatile("s_waitcnt vmcnt(" #n ")" ::: "memory")
; #define PG8_BAR __builtin_amdgcn_s_barrier()
; template <class Epi, class Sched, bool ALIGN_EPI = false, bool SP2 = false>
; __device__ __forceinline__ void gemm_phase(PG8_LAS unsigned char* lds, const Gemm g, const Sched& S, const Epi& E) {
;     ...
;     for (int i = 0; i < 2; ++i) { int R, C; stage_rc(tid * 16 + i * 8192, R, C); const int Rb = Epi::PERM ? ((R & ~31) + perm32(R & 31)) : R;
;         voffA[i] = (unsigned)(R * K + C) * 2u; voffB[i] = (unsigned)(Rb * K + C) * 2u; }
;     const size_t kstep = (size_t)(BK * 2);
;     const size_t hstep = (size_t)HALF * K * 2;
;     const size_t tstep = 2 * hstep;
;     const unsigned ldsw = (unsigned)wid * 1024u;
;     const int aoff = lds_byte(wr * 64 + fr, fq * 8), boff = lds_byte(wc * 32 + fr, fq * 8);
;     ...
;         PG8_STAGE(PG8_SB(1, 0), cB + kstep, voffB); PG8_STAGE(PG8_SA(1, 0), cA + kstep, voffA); PG8_STAGE(PG8_SB(1, 1), cB + hstep + kstep, voffB);
;         PG8_WAIT_V(6); PG8_BAR;
.LBB0_104:
	v_mov_b32_e32 v135, v80
	v_lshl_add_u64 v[8:9], s[46:47], 0, v[134:135]
	v_mov_b32_e32 v131, v80
	v_readlane_b32 s44, v249, 53
	s_lshl_b32 s5, s5, 5
	v_lshl_add_u64 v[10:11], s[46:47], 0, v[130:131]
	v_mov_b32_e32 v137, v80
	v_readlane_b32 s45, v249, 54
	s_and_b32 s55, s5, 0x60
	s_add_i32 m0, s50, 0x18000
	v_lshl_add_u64 v[8:9], v[8:9], 0, s[40:41]
	v_lshl_add_u64 v[12:13], s[44:45], 0, v[136:137]
	v_mov_b32_e32 v133, v80
	s_lshl_b32 s54, s12, 6
	s_lshl_b32 s14, s12, 13
	s_lshl_b32 s5, s55, 7
	s_waitcnt vmcnt(2)
	s_barrier
	global_load_lds_dwordx4 v[8:9], off
	v_lshl_add_u64 v[8:9], v[10:11], 0, s[40:41]
	s_add_i32 m0, s50, 0x1a000
	s_add_i32 s56, s50, 0x8000
	s_add_i32 s57, s50, 0xa000
	v_lshl_add_u64 v[14:15], s[44:45], 0, v[132:133]
	global_load_lds_dwordx4 v[8:9], off
	v_lshl_add_u64 v[8:9], v[12:13], 0, s[40:41]
	s_mov_b32 m0, s56
	s_add_u32 s12, s46, 0x40080
	global_load_lds_dwordx4 v[8:9], off
	v_lshl_add_u64 v[8:9], v[14:15], 0, s[40:41]
	s_mov_b32 m0, s57
	s_addc_u32 s13, s47, 0
	global_load_lds_dwordx4 v[8:9], off
	s_add_i32 m0, s50, 0x1c000
	v_lshl_add_u64 v[8:9], s[12:13], 0, v[134:135]
	global_load_lds_dwordx4 v[8:9], off
	v_lshl_add_u64 v[8:9], s[12:13], 0, v[130:131]
	s_add_i32 m0, s50, 0x1e000
	v_bfe_u32 v142, v0, 4, 2
	global_load_lds_dwordx4 v[8:9], off
	v_and_b32_e32 v81, 15, v0
	v_lshlrev_b32_e32 v7, 4, v142
	v_lshlrev_b32_e32 v0, 2, v0
	v_lshl_or_b32 v7, v81, 6, v7
	v_and_b32_e32 v0, 32, v0
	v_bitop3_b32 v8, v7, s14, v0 bitop3:0xde
	v_bitop3_b32 v143, v7, s5, v0 bitop3:0xde
	v_lshlrev_b32_e32 v0, 14, v5
	v_and_b32_e32 v0, 0xffff8000, v0
	v_lshl_add_u32 v0, v4, 11, v0
	v_and_b32_e32 v4, 1, v5
	v_lshl_or_b32 v0, v4, 6, v0
	v_lshl_add_u32 v138, v6, 1, v0
	v_lshlrev_b32_e32 v0, 14, v1
	v_and_b32_e32 v0, 0xffff8000, v0
	s_waitcnt vmcnt(6)
	v_lshl_add_u32 v0, v2, 11, v0
	v_and_b32_e32 v1, 1, v1
	s_cmpk_lt_u32 s4, 0x100
	v_lshl_or_b32 v0, v1, 6, v0
	v_readlane_b32 s4, v249, 51
	s_cselect_b64 s[12:13], -1, 0
	v_mov_b32_e32 v139, v80
	v_lshl_add_u32 v140, v3, 1, v0
	v_mov_b32_e32 v141, v80
	s_and_b64 vcc, exec, s[10:11]
	s_cbranch_vccz .Lffn_pA
	s_add_u32 s100, s44, 0x40080
	s_addc_u32 s101, s45, 0
	s_add_i32 m0, s50, 0xc000
	s_nop 0
	global_load_lds_dwordx4 v138, s[100:101]
	s_add_i32 m0, s50, 0xe000
	s_nop 0
	global_load_lds_dwordx4 v140, s[100:101]
.Lffn_pA:
	s_mov_b32 s58, 0
	s_mov_b32 s59, -1
	v_add_u32_e32 v144, 0, v8
	v_readlane_b32 s60, v249, 48
	s_mov_b32 s61, s4
	s_barrier
	v_readlane_b32 s5, v249, 52
	s_branch .LBB0_107

; #define PG8_STAGE(bufoff, gbase, voff) do { _Pragma("unroll") for (int _i = 0; _i < 2; ++_i) \
;         __builtin_amdgcn_global_load_lds((const unsigned*)((const char*)(gbase) + (voff)[_i]), (PG8_LAS unsigned*)(lds + (bufoff) + ldsw + _i * 8192), 16, 0, 0); } while (0)
; #define PG8_LDA(dst, b, h) do { _Pragma("unroll") for (int m = 0; m < 4; ++m) _Pragma("unroll") for (int k = 0; k < 2; ++k) dst[m][k] = *(const PG8_LAS bf16x8*)(lds + PG8_SA(b, h) + aoff + m * 2048 + k * 1024); } while (0)
; #define PG8_LDB(dst, b, h) do { _Pragma("unroll") for (int n = 0; n < 2; ++n) _Pragma("unroll") for (int k = 0; k < 2; ++k) dst[n][k] = *(const PG8_LAS bf16x8*)(lds + PG8_SB(b, h) + boff + n * 2048 + k * 1024); } while (0)
; #define PG8_MMA(ai, bj, At, Bt) do { __builtin_amdgcn_s_setprio(1); _Pragma("unroll") for (int m = 0; m < 4; ++m) _Pragma("unroll") for (int n = 0; n < 2; ++n) _Pragma("unroll") for (int k = 0; k < 2; ++k) \
;         acc[ai][bj][m][n] = __builtin_amdgcn_mfma_f32_16x16x32_bf16(Bt[n][k], At[m][k], acc[ai][bj][m][n], 0, 0, 0); __builtin_amdgcn_s_setprio(0); } while (0)
; #define PG8_WAIT_V(n) asm volatile("s_waitcnt vmcnt(" #n ")" ::: "memory")
; #define PG8_WAIT_L(n) asm volatile("s_waitcnt lgkmcnt(" #n ")" ::: "memory")
; #define PG8_BAR __builtin_amdgcn_s_barrier()
; template <class Epi, class Sched, bool ALIGN_EPI = false, bool SP2 = false>
; __device__ __forceinline__ void gemm_phase(PG8_LAS unsigned char* lds, const Gemm g, const Sched& S, const Epi& E) {
;     ...
;             const char* a1 = cA + (size_t)(t + 1) * kstep;
;             const char* a2 = last ? nA : cA + (size_t)(t + 2) * kstep; const char* b2 = last ? nB : cB + (size_t)(t + 2) * kstep;
;             const char* a3 = a2 + kstep; const char* b3 = b2 + kstep;
;             if (last && has_next) S.a_ready(nxt);
;             if constexpr (SP2) {
;             PG8_LDB(B0, 0, 0); PG8_LDB(B1, 0, 1); PG8_SCHED; PG8_LDA(At, 0, 0); PG8_STAGE(PG8_SA(1, 1), a1 + hstep, voffA);
;             PG8_WAIT_V(8); PG8_WAIT_L(0); PG8_BAR; PG8_MMA(0, 0, At, B0); PG8_MMA(0, 1, At, B1); PG8_BAR; PG8_SCHED;
;             PG8_LDA(At, 0, 1); PG8_STAGE(PG8_SB(0, 0), b2, voffB); PG8_STAGE(PG8_SB(0, 1), b2 + hstep, voffB); PG8_STAGE(PG8_SA(0, 0), a2, voffA);
;             PG8_WAIT_V(8); PG8_WAIT_L(0); PG8_BAR; PG8_MMA(1, 0, At, B0); PG8_MMA(1, 1, At, B1); PG8_BAR; PG8_SCHED;
.Lffn_kA:
	s_add_u32 s46, s44, 0xfffc0080
	s_addc_u32 s47, s45, -1
	s_add_u32 s70, s44, 0x100
	s_addc_u32 s71, s45, 0
	s_add_u32 s72, s62, 0x40080
	s_addc_u32 s73, s17, 0
	s_cmp_eq_u32 s66, 12
	s_cselect_b32 s49, s17, s47
	s_cselect_b32 s48, s62, s46
	s_cselect_b32 s47, s15, s65
	s_cselect_b32 s46, s63, s64
	s_cselect_b32 s70, s72, s70
	s_cselect_b32 s71, s73, s71
	s_add_u32 s68, s46, 0x40000
	s_addc_u32 s69, s47, 0
	s_add_u32 s100, s48, 0x40000
	s_addc_u32 s101, s49, 0
	s_add_i32 m0, s39, 0xc000
	s_nop 0
	global_load_lds_dwordx4 v138, s[44:45]
	s_add_i32 m0, s39, 0xe000
	s_nop 0
	global_load_lds_dwordx4 v140, s[44:45]
	v_add_u32_e32 v145, 0x10000, v143
	ds_read_b128 v[146:149], v145
	ds_read_b128 v[150:153], v145 offset:1024
	ds_read_b128 v[154:157], v145 offset:2048
	ds_read_b128 v[158:161], v145 offset:3072
	v_add_u32_e32 v145, 0x14000, v143
	ds_read_b128 v[176:179], v145
	ds_read_b128 v[180:183], v145 offset:1024
	ds_read_b128 v[184:187], v145 offset:2048
	ds_read_b128 v[188:191], v145 offset:3072
	ds_read_b128 v[192:195], v144
	ds_read_b128 v[196:199], v144 offset:1024
	ds_read_b128 v[208:211], v144 offset:2048
	ds_read_b128 v[212:215], v144 offset:3072
	ds_read_b128 v[216:219], v144 offset:4096
	ds_read_b128 v[220:223], v144 offset:5120
	ds_read_b128 v[224:227], v144 offset:6144
	ds_read_b128 v[228:231], v144 offset:7168
	s_waitcnt vmcnt(8)
	s_waitcnt lgkmcnt(0)
	s_setprio 1
	s_barrier
	v_mfma_f32_16x16x32_bf16 v[126:129], v[146:149], v[192:195], v[126:129]
	v_mfma_f32_16x16x32_bf16 v[118:121], v[154:157], v[192:195], v[118:121]
	v_mfma_f32_16x16x32_bf16 v[122:125], v[176:179], v[192:195], v[122:125]
	v_mfma_f32_16x16x32_bf16 v[114:117], v[184:187], v[192:195], v[114:117]
	v_mfma_f32_16x16x32_bf16 v[126:129], v[150:153], v[196:199], v[126:129]
	v_mfma_f32_16x16x32_bf16 v[118:121], v[158:161], v[196:199], v[118:121]
	v_mfma_f32_16x16x32_bf16 v[122:125], v[180:183], v[196:199], v[122:125]
	v_mfma_f32_16x16x32_bf16 v[114:117], v[188:191], v[196:199], v[114:117]
	ds_read_b128 v[192:195], v144 offset:16384
	ds_read_b128 v[196:199], v144 offset:17408
	v_mfma_f32_16x16x32_bf16 v[110:113], v[146:149], v[208:211], v[110:113]
	v_mfma_f32_16x16x32_bf16 v[102:105], v[154:157], v[208:211], v[102:105]
	v_mfma_f32_16x16x32_bf16 v[106:109], v[176:179], v[208:211], v[106:109]
	v_mfma_f32_16x16x32_bf16 v[98:101], v[184:187], v[208:211], v[98:101]
	v_mfma_f32_16x16x32_bf16 v[110:113], v[150:153], v[212:215], v[110:113]
	v_mfma_f32_16x16x32_bf16 v[102:105], v[158:161], v[212:215], v[102:105]
	v_mfma_f32_16x16x32_bf16 v[106:109], v[180:183], v[212:215], v[106:109]
	v_mfma_f32_16x16x32_bf16 v[98:101], v[188:191], v[212:215], v[98:101]
	ds_read_b128 v[208:211], v144 offset:18432
	ds_read_b128 v[212:215], v144 offset:19456
	v_mfma_f32_16x16x32_bf16 v[94:97], v[146:149], v[216:219], v[94:97]
	v_mfma_f32_16x16x32_bf16 v[86:89], v[154:157], v[216:219], v[86:89]
	v_mfma_f32_16x16x32_bf16 v[90:93], v[176:179], v[216:219], v[90:93]
	v_mfma_f32_16x16x32_bf16 v[82:85], v[184:187], v[216:219], v[82:85]
	v_mfma_f32_16x16x32_bf16 v[94:97], v[150:153], v[220:223], v[94:97]
	v_mfma_f32_16x16x32_bf16 v[86:89], v[158:161], v[220:223], v[86:89]
	v_mfma_f32_16x16x32_bf16 v[90:93], v[180:183], v[220:223], v[90:93]
	v_mfma_f32_16x16x32_bf16 v[82:85], v[188:191], v[220:223], v[82:85]
	ds_read_b128 v[216:219], v144 offset:20480
	ds_read_b128 v[220:223], v144 offset:21504
	v_mfma_f32_16x16x32_bf16 v[76:79], v[146:149], v[224:227], v[76:79]
	v_mfma_f32_16x16x32_bf16 v[68:71], v[154:157], v[224:227], v[68:71]
	v_mfma_f32_16x16x32_bf16 v[72:75], v[176:179], v[224:227], v[72:75]
	v_mfma_f32_16x16x32_bf16 v[64:67], v[184:187], v[224:227], v[64:67]
	v_mfma_f32_16x16x32_bf16 v[76:79], v[150:153], v[228:231], v[76:79]
	v_mfma_f32_16x16x32_bf16 v[68:71], v[158:161], v[228:231], v[68:71]
	v_mfma_f32_16x16x32_bf16 v[72:75], v[180:183], v[228:231], v[72:75]
	v_mfma_f32_16x16x32_bf16 v[64:67], v[188:191], v[228:231], v[64:67]
	ds_read_b128 v[224:227], v144 offset:22528
	ds_read_b128 v[228:231], v144 offset:23552
	s_waitcnt lgkmcnt(6)
	v_mfma_f32_16x16x32_bf16 v[60:63], v[146:149], v[192:195], v[60:63]
	v_mfma_f32_16x16x32_bf16 v[52:55], v[154:157], v[192:195], v[52:55]
	v_mfma_f32_16x16x32_bf16 v[56:59], v[176:179], v[192:195], v[56:59]
	v_mfma_f32_16x16x32_bf16 v[48:51], v[184:187], v[192:195], v[48:51]
	v_mfma_f32_16x16x32_bf16 v[60:63], v[150:153], v[196:199], v[60:63]
	v_mfma_f32_16x16x32_bf16 v[52:55], v[158:161], v[196:199], v[52:55]
	v_mfma_f32_16x16x32_bf16 v[56:59], v[180:183], v[196:199], v[56:59]
	v_mfma_f32_16x16x32_bf16 v[48:51], v[188:191], v[196:199], v[48:51]
	s_waitcnt lgkmcnt(4)
	v_mfma_f32_16x16x32_bf16 v[44:47], v[146:149], v[208:211], v[44:47]
	v_mfma_f32_16x16x32_bf16 v[36:39], v[154:157], v[208:211], v[36:39]
	v_mfma_f32_16x16x32_bf16 v[40:43], v[176:179], v[208:211], v[40:43]
	v_mfma_f32_16x16x32_bf16 v[32:35], v[184:187], v[208:211], v[32:35]
	v_mfma_f32_16x16x32_bf16 v[44:47], v[150:153], v[212:215], v[44:47]
	v_mfma_f32_16x16x32_bf16 v[36:39], v[158:161], v[212:215], v[36:39]
	v_mfma_f32_16x16x32_bf16 v[40:43], v[180:183], v[212:215], v[40:43]
	v_mfma_f32_16x16x32_bf16 v[32:35], v[188:191], v[212:215], v[32:35]
	s_waitcnt lgkmcnt(2)
	v_mfma_f32_16x16x32_bf16 v[28:31], v[146:149], v[216:219], v[28:31]
	v_mfma_f32_16x16x32_bf16 v[20:23], v[154:157], v[216:219], v[20:23]
	v_mfma_f32_16x16x32_bf16 v[24:27], v[176:179], v[216:219], v[24:27]
	v_mfma_f32_16x16x32_bf16 v[16:19], v[184:187], v[216:219], v[16:19]
	v_mfma_f32_16x16x32_bf16 v[28:31], v[150:153], v[220:223], v[28:31]
	v_mfma_f32_16x16x32_bf16 v[20:23], v[158:161], v[220:223], v[20:23]
	v_mfma_f32_16x16x32_bf16 v[24:27], v[180:183], v[220:223], v[24:27]
	v_mfma_f32_16x16x32_bf16 v[16:19], v[188:191], v[220:223], v[16:19]
	s_waitcnt lgkmcnt(0)
	v_mfma_f32_16x16x32_bf16 v[12:15], v[146:149], v[224:227], v[12:15]
	v_mfma_f32_16x16x32_bf16 v[4:7], v[154:157], v[224:227], v[4:7]
	v_mfma_f32_16x16x32_bf16 v[8:11], v[176:179], v[224:227], v[8:11]
	v_mfma_f32_16x16x32_bf16 v[0:3], v[184:187], v[224:227], v[0:3]
	v_mfma_f32_16x16x32_bf16 v[12:15], v[150:153], v[228:231], v[12:15]
	v_mfma_f32_16x16x32_bf16 v[4:7], v[158:161], v[228:231], v[4:7]
	v_mfma_f32_16x16x32_bf16 v[8:11], v[180:183], v[228:231], v[8:11]
	v_mfma_f32_16x16x32_bf16 v[0:3], v[188:191], v[228:231], v[0:3]
	s_waitcnt vmcnt(2)
	s_setprio 0
	s_barrier
; #define PG8_STAGE(bufoff, gbase, voff) do { _Pragma("unroll") for (int _i = 0; _i < 2; ++_i) \
;         __builtin_amdgcn_global_load_lds((const unsigned*)((const char*)(gbase) + (voff)[_i]), (PG8_LAS unsigned*)(lds + (bufoff) + ldsw + _i * 8192), 16, 0, 0); } while (0)
; #define PG8_LDA(dst, b, h) do { _Pragma("unroll") for (int m = 0; m < 4; ++m) _Pragma("unroll") for (int k = 0; k < 2; ++k) dst[m][k] = *(const PG8_LAS bf16x8*)(lds + PG8_SA(b, h) + aoff + m * 2048 + k * 1024); } while (0)
; #define PG8_LDB(dst, b, h) do { _Pragma("unroll") for (int n = 0; n < 2; ++n) _Pragma("unroll") for (int k = 0; k < 2; ++k) dst[n][k] = *(const PG8_LAS bf16x8*)(lds + PG8_SB(b, h) + boff + n * 2048 + k * 1024); } while (0)
; #define PG8_MMA(ai, bj, At, Bt) do { __builtin_amdgcn_s_setprio(1); _Pragma("unroll") for (int m = 0; m < 4; ++m) _Pragma("unroll") for (int n = 0; n < 2; ++n) _Pragma("unroll") for (int k = 0; k < 2; ++k) \
;         acc[ai][bj][m][n] = __builtin_amdgcn_mfma_f32_16x16x32_bf16(Bt[n][k], At[m][k], acc[ai][bj][m][n], 0, 0, 0); __builtin_amdgcn_s_setprio(0); } while (0)
; #define PG8_WAIT_V(n) asm volatile("s_waitcnt vmcnt(" #n ")" ::: "memory")
; #define PG8_WAIT_L(n) asm volatile("s_waitcnt lgkmcnt(" #n ")" ::: "memory")
; #define PG8_BAR __builtin_amdgcn_s_barrier()
; #define PG8_SCHED __builtin_amdgcn_sched_barrier(0)
; template <class Epi, class Sched, bool ALIGN_EPI = false, bool SP2 = false>
; __device__ __forceinline__ void gemm_phase(PG8_LAS unsigned char* lds, const Gemm g, const Sched& S, const Epi& E) {
;     ...
;             PG8_LDA(At, 0, 1); PG8_STAGE(PG8_SB(0, 0), b2, voffB); PG8_STAGE(PG8_SB(0, 1), b2 + hstep, voffB); PG8_STAGE(PG8_SA(0, 0), a2, voffA);
;             PG8_WAIT_V(8); PG8_WAIT_L(0); PG8_BAR; PG8_MMA(1, 0, At, B0); PG8_MMA(1, 1, At, B1); PG8_BAR; PG8_SCHED;
;             PG8_LDB(B0, 1, 0); PG8_LDB(B1, 1, 1); PG8_SCHED; PG8_LDA(At, 1, 0); PG8_STAGE(PG8_SA(0, 1), a2 + hstep, voffA);
;             PG8_WAIT_V(8); PG8_WAIT_L(0); PG8_BAR; PG8_MMA(0, 0, At, B0); PG8_MMA(0, 1, At, B1); PG8_BAR; PG8_SCHED;
;             PG8_LDA(At, 1, 1); PG8_STAGE(PG8_SB(1, 0), b3, voffB); PG8_STAGE(PG8_SB(1, 1), b3 + hstep, voffB); PG8_STAGE(PG8_SA(1, 0), a3, voffA);
	s_add_i32 m0, s39, 0x10000
	s_nop 0
	global_load_lds_dwordx4 v134, s[46:47]
	s_add_i32 m0, s39, 0x12000
	s_nop 0
	global_load_lds_dwordx4 v130, s[46:47]
	s_add_i32 m0, s39, 0x14000
	s_nop 0
	global_load_lds_dwordx4 v134, s[68:69]
	s_add_i32 m0, s39, 0x16000
	s_nop 0
	global_load_lds_dwordx4 v130, s[68:69]
	s_add_i32 m0, s39, 0x0
	s_nop 0
	global_load_lds_dwordx4 v136, s[48:49]
	s_add_i32 m0, s39, 0x2000
	s_nop 0
	global_load_lds_dwordx4 v132, s[48:49]
	v_add_u32_e32 v145, 0x18000, v143
	ds_read_b128 v[146:149], v145
	ds_read_b128 v[150:153], v145 offset:1024
	ds_read_b128 v[154:157], v145 offset:2048
	ds_read_b128 v[158:161], v145 offset:3072
	v_add_u32_e32 v145, 0x1c000, v143
	ds_read_b128 v[176:179], v145
	ds_read_b128 v[180:183], v145 offset:1024
	ds_read_b128 v[184:187], v145 offset:2048
	ds_read_b128 v[188:191], v145 offset:3072
	ds_read_b128 v[192:195], v144 offset:32768
	ds_read_b128 v[196:199], v144 offset:33792
	ds_read_b128 v[208:211], v144 offset:34816
	ds_read_b128 v[212:215], v144 offset:35840
	ds_read_b128 v[216:219], v144 offset:36864
	ds_read_b128 v[220:223], v144 offset:37888
	ds_read_b128 v[224:227], v144 offset:38912
	ds_read_b128 v[228:231], v144 offset:39936
	s_waitcnt lgkmcnt(0)
	s_setprio 1
	s_barrier
	v_mfma_f32_16x16x32_bf16 v[126:129], v[146:149], v[192:195], v[126:129]
	s_add_i32 m0, s39, 0x4000
	v_mfma_f32_16x16x32_bf16 v[118:121], v[154:157], v[192:195], v[118:121]
	global_load_lds_dwordx4 v136, s[100:101]
	v_mfma_f32_16x16x32_bf16 v[122:125], v[176:179], v[192:195], v[122:125]
	v_mfma_f32_16x16x32_bf16 v[114:117], v[184:187], v[192:195], v[114:117]
	s_add_i32 m0, s39, 0x6000
	v_mfma_f32_16x16x32_bf16 v[126:129], v[150:153], v[196:199], v[126:129]
	global_load_lds_dwordx4 v132, s[100:101]
	v_mfma_f32_16x16x32_bf16 v[118:121], v[158:161], v[196:199], v[118:121]
	v_mfma_f32_16x16x32_bf16 v[122:125], v[180:183], v[196:199], v[122:125]
	v_mfma_f32_16x16x32_bf16 v[114:117], v[188:191], v[196:199], v[114:117]
	v_mfma_f32_16x16x32_bf16 v[110:113], v[146:149], v[208:211], v[110:113]
	v_mfma_f32_16x16x32_bf16 v[102:105], v[154:157], v[208:211], v[102:105]
	v_mfma_f32_16x16x32_bf16 v[106:109], v[176:179], v[208:211], v[106:109]
	v_mfma_f32_16x16x32_bf16 v[98:101], v[184:187], v[208:211], v[98:101]
	v_mfma_f32_16x16x32_bf16 v[110:113], v[150:153], v[212:215], v[110:113]
	v_mfma_f32_16x16x32_bf16 v[102:105], v[158:161], v[212:215], v[102:105]
	v_mfma_f32_16x16x32_bf16 v[106:109], v[180:183], v[212:215], v[106:109]
	v_mfma_f32_16x16x32_bf16 v[98:101], v[188:191], v[212:215], v[98:101]
	v_mfma_f32_16x16x32_bf16 v[94:97], v[146:149], v[216:219], v[94:97]
	v_mfma_f32_16x16x32_bf16 v[86:89], v[154:157], v[216:219], v[86:89]
	v_mfma_f32_16x16x32_bf16 v[90:93], v[176:179], v[216:219], v[90:93]
	v_mfma_f32_16x16x32_bf16 v[82:85], v[184:187], v[216:219], v[82:85]
	v_mfma_f32_16x16x32_bf16 v[94:97], v[150:153], v[220:223], v[94:97]
	v_mfma_f32_16x16x32_bf16 v[86:89], v[158:161], v[220:223], v[86:89]
	v_mfma_f32_16x16x32_bf16 v[90:93], v[180:183], v[220:223], v[90:93]
	v_mfma_f32_16x16x32_bf16 v[82:85], v[188:191], v[220:223], v[82:85]
	v_mfma_f32_16x16x32_bf16 v[76:79], v[146:149], v[224:227], v[76:79]
	v_mfma_f32_16x16x32_bf16 v[68:71], v[154:157], v[224:227], v[68:71]
	v_mfma_f32_16x16x32_bf16 v[72:75], v[176:179], v[224:227], v[72:75]
	v_mfma_f32_16x16x32_bf16 v[64:67], v[184:187], v[224:227], v[64:67]
	v_mfma_f32_16x16x32_bf16 v[76:79], v[150:153], v[228:231], v[76:79]
	v_mfma_f32_16x16x32_bf16 v[68:71], v[158:161], v[228:231], v[68:71]
	v_mfma_f32_16x16x32_bf16 v[72:75], v[180:183], v[228:231], v[72:75]
	v_mfma_f32_16x16x32_bf16 v[64:67], v[188:191], v[228:231], v[64:67]
	s_waitcnt vmcnt(8)
	s_setprio 0
	s_barrier
	s_add_u32 s46, s46, 0x80
	s_addc_u32 s47, s47, 0
	s_add_u32 s68, s68, 0x80
	s_addc_u32 s69, s69, 0
	s_add_u32 s48, s48, 0x80
	s_addc_u32 s49, s49, 0
	s_add_i32 m0, s39, 0x18000
	s_nop 0
	global_load_lds_dwordx4 v134, s[46:47]
	s_add_i32 m0, s39, 0x1a000
	s_nop 0
	global_load_lds_dwordx4 v130, s[46:47]
	s_add_i32 m0, s39, 0x1c000
	s_nop 0
	global_load_lds_dwordx4 v134, s[68:69]
	s_add_i32 m0, s39, 0x1e000
	s_nop 0
	global_load_lds_dwordx4 v130, s[68:69]
	s_add_i32 m0, s39, 0x8000
	s_nop 0
	global_load_lds_dwordx4 v136, s[48:49]
	s_add_i32 m0, s39, 0xa000
	s_nop 0
	global_load_lds_dwordx4 v132, s[48:49]
	ds_read_b128 v[192:195], v144 offset:49152
	ds_read_b128 v[196:199], v144 offset:50176
	ds_read_b128 v[208:211], v144 offset:51200
	ds_read_b128 v[212:215], v144 offset:52224
	ds_read_b128 v[216:219], v144 offset:53248
	ds_read_b128 v[220:223], v144 offset:54272
	ds_read_b128 v[224:227], v144 offset:55296
	ds_read_b128 v[228:231], v144 offset:56320
	s_waitcnt lgkmcnt(0)
	s_setprio 1
	s_barrier
; #define PG8_STAGE(bufoff, gbase, voff) do { _Pragma("unroll") for (int _i = 0; _i < 2; ++_i) \
;         __builtin_amdgcn_global_load_lds((const unsigned*)((const char*)(gbase) + (voff)[_i]), (PG8_LAS unsigned*)(lds + (bufoff) + ldsw + _i * 8192), 16, 0, 0); } while (0)
; #define PG8_LDA(dst, b, h) do { _Pragma("unroll") for (int m = 0; m < 4; ++m) _Pragma("unroll") for (int k = 0; k < 2; ++k) dst[m][k] = *(const PG8_LAS bf16x8*)(lds + PG8_SA(b, h) + aoff + m * 2048 + k * 1024); } while (0)
; #define PG8_LDB(dst, b, h) do { _Pragma("unroll") for (int n = 0; n < 2; ++n) _Pragma("unroll") for (int k = 0; k < 2; ++k) dst[n][k] = *(const PG8_LAS bf16x8*)(lds + PG8_SB(b, h) + boff + n * 2048 + k * 1024); } while (0)
; #define PG8_MMA(ai, bj, At, Bt) do { __builtin_amdgcn_s_setprio(1); _Pragma("unroll") for (int m = 0; m < 4; ++m) _Pragma("unroll") for (int n = 0; n < 2; ++n) _Pragma("unroll") for (int k = 0; k < 2; ++k) \
;         acc[ai][bj][m][n] = __builtin_amdgcn_mfma_f32_16x16x32_bf16(Bt[n][k], At[m][k], acc[ai][bj][m][n], 0, 0, 0); __builtin_amdgcn_s_setprio(0); } while (0)
; template <class Epi, class Sched, bool ALIGN_EPI = false, bool SP2 = false>
; __device__ __forceinline__ void gemm_phase(PG8_LAS unsigned char* lds, const Gemm g, const Sched& S, const Epi& E) {
;     ...
;         for (int t = 0; t < nt; t += 2) {
;             if constexpr (Epi::PF_TRIPS > 0) { if (t == nt - 2 * Epi::PF_TRIPS) E.prefetch(cur, tid, lds + STAGE_BYTES + wid * 512); }
;             const bool last = (t == nt - 2);
;             const char* a1 = cA + (size_t)(t + 1) * kstep;
;             const char* a2 = last ? nA : cA + (size_t)(t + 2) * kstep; const char* b2 = last ? nB : cB + (size_t)(t + 2) * kstep;
;             const char* a3 = a2 + kstep; const char* b3 = b2 + kstep;
;             if (last && has_next) S.a_ready(nxt);
;             if constexpr (SP2) {
;             PG8_LDB(B0, 0, 0); PG8_LDB(B1, 0, 1); PG8_SCHED; PG8_LDA(At, 0, 0); PG8_STAGE(PG8_SA(1, 1), a1 + hstep, voffA);
;             PG8_WAIT_V(8); PG8_WAIT_L(0); PG8_BAR; PG8_MMA(0, 0, At, B0); PG8_MMA(0, 1, At, B1); PG8_BAR; PG8_SCHED;
;     ...
;             PG8_LDA(At, 1, 1); PG8_STAGE(PG8_SB(1, 0), b3, voffB); PG8_STAGE(PG8_SB(1, 1), b3 + hstep, voffB); PG8_STAGE(PG8_SA(1, 0), a3, voffA);
;             PG8_WAIT_V(8); PG8_WAIT_L(0); PG8_BAR; PG8_MMA(1, 0, At, B0); PG8_MMA(1, 1, At, B1); PG8_BAR; PG8_SCHED;
	v_mfma_f32_16x16x32_bf16 v[60:63], v[146:149], v[192:195], v[60:63]
	v_mfma_f32_16x16x32_bf16 v[52:55], v[154:157], v[192:195], v[52:55]
	v_mfma_f32_16x16x32_bf16 v[56:59], v[176:179], v[192:195], v[56:59]
	v_mfma_f32_16x16x32_bf16 v[48:51], v[184:187], v[192:195], v[48:51]
	v_mfma_f32_16x16x32_bf16 v[60:63], v[150:153], v[196:199], v[60:63]
	v_mfma_f32_16x16x32_bf16 v[52:55], v[158:161], v[196:199], v[52:55]
	v_mfma_f32_16x16x32_bf16 v[56:59], v[180:183], v[196:199], v[56:59]
	v_mfma_f32_16x16x32_bf16 v[48:51], v[188:191], v[196:199], v[48:51]
	v_mfma_f32_16x16x32_bf16 v[44:47], v[146:149], v[208:211], v[44:47]
	v_mfma_f32_16x16x32_bf16 v[36:39], v[154:157], v[208:211], v[36:39]
	v_mfma_f32_16x16x32_bf16 v[40:43], v[176:179], v[208:211], v[40:43]
	v_mfma_f32_16x16x32_bf16 v[32:35], v[184:187], v[208:211], v[32:35]
	v_mfma_f32_16x16x32_bf16 v[44:47], v[150:153], v[212:215], v[44:47]
	v_mfma_f32_16x16x32_bf16 v[36:39], v[158:161], v[212:215], v[36:39]
	v_mfma_f32_16x16x32_bf16 v[40:43], v[180:183], v[212:215], v[40:43]
	v_mfma_f32_16x16x32_bf16 v[32:35], v[188:191], v[212:215], v[32:35]
	v_mfma_f32_16x16x32_bf16 v[28:31], v[146:149], v[216:219], v[28:31]
	v_mfma_f32_16x16x32_bf16 v[20:23], v[154:157], v[216:219], v[20:23]
	v_mfma_f32_16x16x32_bf16 v[24:27], v[176:179], v[216:219], v[24:27]
	v_mfma_f32_16x16x32_bf16 v[16:19], v[184:187], v[216:219], v[16:19]
	v_mfma_f32_16x16x32_bf16 v[28:31], v[150:153], v[220:223], v[28:31]
	v_mfma_f32_16x16x32_bf16 v[20:23], v[158:161], v[220:223], v[20:23]
	v_mfma_f32_16x16x32_bf16 v[24:27], v[180:183], v[220:223], v[24:27]
	v_mfma_f32_16x16x32_bf16 v[16:19], v[188:191], v[220:223], v[16:19]
	v_mfma_f32_16x16x32_bf16 v[12:15], v[146:149], v[224:227], v[12:15]
	v_mfma_f32_16x16x32_bf16 v[4:7], v[154:157], v[224:227], v[4:7]
	v_mfma_f32_16x16x32_bf16 v[8:11], v[176:179], v[224:227], v[8:11]
	v_mfma_f32_16x16x32_bf16 v[0:3], v[184:187], v[224:227], v[0:3]
	v_mfma_f32_16x16x32_bf16 v[12:15], v[150:153], v[228:231], v[12:15]
	v_mfma_f32_16x16x32_bf16 v[4:7], v[158:161], v[228:231], v[4:7]
	v_mfma_f32_16x16x32_bf16 v[8:11], v[180:183], v[228:231], v[8:11]
	v_mfma_f32_16x16x32_bf16 v[0:3], v[188:191], v[228:231], v[0:3]
	s_waitcnt vmcnt(8)
	s_setprio 0
	s_barrier
	s_add_i32 s66, s66, 2
	s_add_u32 s44, s44, 0x100
	s_addc_u32 s45, s45, 0
	s_add_u32 s64, s64, 0x100
	s_addc_u32 s65, s65, 0
	s_cmp_gt_u32 s66, 13
	s_cbranch_scc0 .Lffn_kA
	s_branch .Lffn_kdone
.Lffn_kB:
	s_add_u32 s46, s44, 0xfffc0080
	s_addc_u32 s47, s45, -1
	s_add_u32 s70, s44, 0x100
	s_addc_u32 s71, s45, 0
	s_add_u32 s72, s62, 0x40080
	s_addc_u32 s73, s17, 0
	s_cmp_eq_u32 s66, 12
	s_cselect_b32 s49, s17, s47
	s_cselect_b32 s48, s62, s46
	s_cselect_b32 s47, s15, s65
	s_cselect_b32 s46, s63, s64
	s_cselect_b32 s70, s72, s70
	s_cselect_b32 s71, s73, s71
	s_add_u32 s68, s46, 0x40000
	s_addc_u32 s69, s47, 0
	s_add_u32 s100, s48, 0x40000
	s_addc_u32 s101, s49, 0
	v_add_u32_e32 v145, 0x10000, v143
	ds_read_b128 v[146:149], v145
	ds_read_b128 v[150:153], v145 offset:1024
	ds_read_b128 v[154:157], v145 offset:2048
	ds_read_b128 v[158:161], v145 offset:3072
	v_add_u32_e32 v145, 0x14000, v143
	ds_read_b128 v[176:179], v145
	ds_read_b128 v[180:183], v145 offset:1024
	ds_read_b128 v[184:187], v145 offset:2048
	ds_read_b128 v[188:191], v145 offset:3072
	ds_read_b128 v[192:195], v144
	ds_read_b128 v[196:199], v144 offset:1024
	ds_read_b128 v[208:211], v144 offset:2048
	ds_read_b128 v[212:215], v144 offset:3072
	ds_read_b128 v[216:219], v144 offset:4096
	ds_read_b128 v[220:223], v144 offset:5120
	ds_read_b128 v[224:227], v144 offset:6144
	ds_read_b128 v[228:231], v144 offset:7168
	s_waitcnt vmcnt(2)
	s_waitcnt lgkmcnt(0)
	s_setprio 1
	s_barrier
	v_mfma_f32_16x16x32_bf16 v[126:129], v[146:149], v[192:195], v[126:129]
	s_add_i32 m0, s39, 0x10000
	v_mfma_f32_16x16x32_bf16 v[118:121], v[154:157], v[192:195], v[118:121]
	global_load_lds_dwordx4 v134, s[46:47]
	v_mfma_f32_16x16x32_bf16 v[122:125], v[176:179], v[192:195], v[122:125]
	v_mfma_f32_16x16x32_bf16 v[114:117], v[184:187], v[192:195], v[114:117]
	s_add_i32 m0, s39, 0x12000
	v_mfma_f32_16x16x32_bf16 v[126:129], v[150:153], v[196:199], v[126:129]
	global_load_lds_dwordx4 v130, s[46:47]
	v_mfma_f32_16x16x32_bf16 v[118:121], v[158:161], v[196:199], v[118:121]
	v_mfma_f32_16x16x32_bf16 v[122:125], v[180:183], v[196:199], v[122:125]
	v_mfma_f32_16x16x32_bf16 v[114:117], v[188:191], v[196:199], v[114:117]
	ds_read_b128 v[192:195], v144 offset:16384
	ds_read_b128 v[196:199], v144 offset:17408
	v_mfma_f32_16x16x32_bf16 v[110:113], v[146:149], v[208:211], v[110:113]
	v_mfma_f32_16x16x32_bf16 v[102:105], v[154:157], v[208:211], v[102:105]
	s_add_i32 m0, s39, 0x14000
	v_mfma_f32_16x16x32_bf16 v[106:109], v[176:179], v[208:211], v[106:109]
	global_load_lds_dwordx4 v134, s[68:69]
	v_mfma_f32_16x16x32_bf16 v[98:101], v[184:187], v[208:211], v[98:101]
	v_mfma_f32_16x16x32_bf16 v[110:113], v[150:153], v[212:215], v[110:113]
	s_add_i32 m0, s39, 0x16000
	v_mfma_f32_16x16x32_bf16 v[102:105], v[158:161], v[212:215], v[102:105]
	global_load_lds_dwordx4 v130, s[68:69]
	v_mfma_f32_16x16x32_bf16 v[106:109], v[180:183], v[212:215], v[106:109]
	v_mfma_f32_16x16x32_bf16 v[98:101], v[188:191], v[212:215], v[98:101]
	ds_read_b128 v[208:211], v144 offset:18432
	ds_read_b128 v[212:215], v144 offset:19456
	s_add_i32 m0, s39, 0x0
	v_mfma_f32_16x16x32_bf16 v[94:97], v[146:149], v[216:219], v[94:97]
	global_load_lds_dwordx4 v136, s[48:49]
	v_mfma_f32_16x16x32_bf16 v[86:89], v[154:157], v[216:219], v[86:89]
	v_mfma_f32_16x16x32_bf16 v[90:93], v[176:179], v[216:219], v[90:93]
	s_add_i32 m0, s39, 0x2000
	v_mfma_f32_16x16x32_bf16 v[82:85], v[184:187], v[216:219], v[82:85]
	global_load_lds_dwordx4 v132, s[48:49]
	v_mfma_f32_16x16x32_bf16 v[94:97], v[150:153], v[220:223], v[94:97]
	v_mfma_f32_16x16x32_bf16 v[86:89], v[158:161], v[220:223], v[86:89]
	v_mfma_f32_16x16x32_bf16 v[90:93], v[180:183], v[220:223], v[90:93]
	v_mfma_f32_16x16x32_bf16 v[82:85], v[188:191], v[220:223], v[82:85]
	ds_read_b128 v[216:219], v144 offset:20480
	ds_read_b128 v[220:223], v144 offset:21504
	v_mfma_f32_16x16x32_bf16 v[76:79], v[146:149], v[224:227], v[76:79]
	v_mfma_f32_16x16x32_bf16 v[68:71], v[154:157], v[224:227], v[68:71]
	v_mfma_f32_16x16x32_bf16 v[72:75], v[176:179], v[224:227], v[72:75]
	v_mfma_f32_16x16x32_bf16 v[64:67], v[184:187], v[224:227], v[64:67]
	v_mfma_f32_16x16x32_bf16 v[76:79], v[150:153], v[228:231], v[76:79]
	v_mfma_f32_16x16x32_bf16 v[68:71], v[158:161], v[228:231], v[68:71]
	v_mfma_f32_16x16x32_bf16 v[72:75], v[180:183], v[228:231], v[72:75]
	v_mfma_f32_16x16x32_bf16 v[64:67], v[188:191], v[228:231], v[64:67]
	ds_read_b128 v[224:227], v144 offset:22528
	ds_read_b128 v[228:231], v144 offset:23552
	s_waitcnt lgkmcnt(6)
; #define PG8_STAGE(bufoff, gbase, voff) do { _Pragma("unroll") for (int _i = 0; _i < 2; ++_i) \
;         __builtin_amdgcn_global_load_lds((const unsigned*)((const char*)(gbase) + (voff)[_i]), (PG8_LAS unsigned*)(lds + (bufoff) + ldsw + _i * 8192), 16, 0, 0); } while (0)
; #define PG8_LDA(dst, b, h) do { _Pragma("unroll") for (int m = 0; m < 4; ++m) _Pragma("unroll") for (int k = 0; k < 2; ++k) dst[m][k] = *(const PG8_LAS bf16x8*)(lds + PG8_SA(b, h) + aoff + m * 2048 + k * 1024); } while (0)
; #define PG8_LDB(dst, b, h) do { _Pragma("unroll") for (int n = 0; n < 2; ++n) _Pragma("unroll") for (int k = 0; k < 2; ++k) dst[n][k] = *(const PG8_LAS bf16x8*)(lds + PG8_SB(b, h) + boff + n * 2048 + k * 1024); } while (0)
; #define PG8_MMA(ai, bj, At, Bt) do { __builtin_amdgcn_s_setprio(1); _Pragma("unroll") for (int m = 0; m < 4; ++m) _Pragma("unroll") for (int n = 0; n < 2; ++n) _Pragma("unroll") for (int k = 0; k < 2; ++k) \
;         acc[ai][bj][m][n] = __builtin_amdgcn_mfma_f32_16x16x32_bf16(Bt[n][k], At[m][k], acc[ai][bj][m][n], 0, 0, 0); __builtin_amdgcn_s_setprio(0); } while (0)
; #define PG8_WAIT_V(n) asm volatile("s_waitcnt vmcnt(" #n ")" ::: "memory")
; #define PG8_WAIT_L(n) asm volatile("s_waitcnt lgkmcnt(" #n ")" ::: "memory")
; #define PG8_BAR __builtin_amdgcn_s_barrier()
; #define PG8_SCHED __builtin_amdgcn_sched_barrier(0)
; template <class Epi, class Sched, bool ALIGN_EPI = false, bool SP2 = false>
; __device__ __forceinline__ void gemm_phase(PG8_LAS unsigned char* lds, const Gemm g, const Sched& S, const Epi& E) {
;     ...
;             PG8_WAIT_V(8); PG8_WAIT_L(0); PG8_BAR; PG8_MMA(0, 0, At, B0); PG8_MMA(0, 1, At, B1); PG8_BAR; PG8_SCHED;
;             PG8_LDA(At, 0, 1); PG8_STAGE(PG8_SB(0, 0), b2, voffB); PG8_STAGE(PG8_SB(0, 1), b2 + hstep, voffB); PG8_STAGE(PG8_SA(0, 0), a2, voffA);
;             PG8_WAIT_V(8); PG8_WAIT_L(0); PG8_BAR; PG8_MMA(1, 0, At, B0); PG8_MMA(1, 1, At, B1); PG8_BAR; PG8_SCHED;
;             PG8_LDB(B0, 1, 0); PG8_LDB(B1, 1, 1); PG8_SCHED; PG8_LDA(At, 1, 0); PG8_STAGE(PG8_SA(0, 1), a2 + hstep, voffA);
	v_mfma_f32_16x16x32_bf16 v[60:63], v[146:149], v[192:195], v[60:63]
	v_mfma_f32_16x16x32_bf16 v[52:55], v[154:157], v[192:195], v[52:55]
	v_mfma_f32_16x16x32_bf16 v[56:59], v[176:179], v[192:195], v[56:59]
	v_mfma_f32_16x16x32_bf16 v[48:51], v[184:187], v[192:195], v[48:51]
	v_mfma_f32_16x16x32_bf16 v[60:63], v[150:153], v[196:199], v[60:63]
	v_mfma_f32_16x16x32_bf16 v[52:55], v[158:161], v[196:199], v[52:55]
	v_mfma_f32_16x16x32_bf16 v[56:59], v[180:183], v[196:199], v[56:59]
	v_mfma_f32_16x16x32_bf16 v[48:51], v[188:191], v[196:199], v[48:51]
	s_waitcnt lgkmcnt(4)
	v_mfma_f32_16x16x32_bf16 v[44:47], v[146:149], v[208:211], v[44:47]
	v_mfma_f32_16x16x32_bf16 v[36:39], v[154:157], v[208:211], v[36:39]
	v_mfma_f32_16x16x32_bf16 v[40:43], v[176:179], v[208:211], v[40:43]
	v_mfma_f32_16x16x32_bf16 v[32:35], v[184:187], v[208:211], v[32:35]
	v_mfma_f32_16x16x32_bf16 v[44:47], v[150:153], v[212:215], v[44:47]
	v_mfma_f32_16x16x32_bf16 v[36:39], v[158:161], v[212:215], v[36:39]
	v_mfma_f32_16x16x32_bf16 v[40:43], v[180:183], v[212:215], v[40:43]
	v_mfma_f32_16x16x32_bf16 v[32:35], v[188:191], v[212:215], v[32:35]
	s_waitcnt lgkmcnt(2)
	v_mfma_f32_16x16x32_bf16 v[28:31], v[146:149], v[216:219], v[28:31]
	v_mfma_f32_16x16x32_bf16 v[20:23], v[154:157], v[216:219], v[20:23]
	v_mfma_f32_16x16x32_bf16 v[24:27], v[176:179], v[216:219], v[24:27]
	v_mfma_f32_16x16x32_bf16 v[16:19], v[184:187], v[216:219], v[16:19]
	v_mfma_f32_16x16x32_bf16 v[28:31], v[150:153], v[220:223], v[28:31]
	v_mfma_f32_16x16x32_bf16 v[20:23], v[158:161], v[220:223], v[20:23]
	v_mfma_f32_16x16x32_bf16 v[24:27], v[180:183], v[220:223], v[24:27]
	v_mfma_f32_16x16x32_bf16 v[16:19], v[188:191], v[220:223], v[16:19]
	s_waitcnt lgkmcnt(0)
	v_mfma_f32_16x16x32_bf16 v[12:15], v[146:149], v[224:227], v[12:15]
	v_mfma_f32_16x16x32_bf16 v[4:7], v[154:157], v[224:227], v[4:7]
	v_mfma_f32_16x16x32_bf16 v[8:11], v[176:179], v[224:227], v[8:11]
	v_mfma_f32_16x16x32_bf16 v[0:3], v[184:187], v[224:227], v[0:3]
	v_mfma_f32_16x16x32_bf16 v[12:15], v[150:153], v[228:231], v[12:15]
	v_mfma_f32_16x16x32_bf16 v[4:7], v[158:161], v[228:231], v[4:7]
	v_mfma_f32_16x16x32_bf16 v[8:11], v[180:183], v[228:231], v[8:11]
	v_mfma_f32_16x16x32_bf16 v[0:3], v[188:191], v[228:231], v[0:3]
	s_setprio 0
	s_barrier
	s_add_i32 m0, s39, 0x4000
	s_nop 0
	global_load_lds_dwordx4 v136, s[100:101]
	s_add_i32 m0, s39, 0x6000
	s_nop 0
	global_load_lds_dwordx4 v132, s[100:101]
	s_add_u32 s46, s46, 0x80
	s_addc_u32 s47, s47, 0
	s_add_u32 s68, s68, 0x80
	s_addc_u32 s69, s69, 0
	s_add_u32 s48, s48, 0x80
	s_addc_u32 s49, s49, 0
	v_add_u32_e32 v145, 0x18000, v143
	ds_read_b128 v[146:149], v145
	ds_read_b128 v[150:153], v145 offset:1024
	ds_read_b128 v[154:157], v145 offset:2048
	ds_read_b128 v[158:161], v145 offset:3072
	v_add_u32_e32 v145, 0x1c000, v143
	ds_read_b128 v[176:179], v145
	ds_read_b128 v[180:183], v145 offset:1024
	ds_read_b128 v[184:187], v145 offset:2048
	ds_read_b128 v[188:191], v145 offset:3072
	ds_read_b128 v[192:195], v144 offset:32768
	ds_read_b128 v[196:199], v144 offset:33792
	ds_read_b128 v[208:211], v144 offset:34816
	ds_read_b128 v[212:215], v144 offset:35840
	ds_read_b128 v[216:219], v144 offset:36864
	ds_read_b128 v[220:223], v144 offset:37888
	ds_read_b128 v[224:227], v144 offset:38912
	ds_read_b128 v[228:231], v144 offset:39936
	s_waitcnt vmcnt(8)
	s_waitcnt lgkmcnt(0)
	s_setprio 1
	s_barrier
; #define PG8_STAGE(bufoff, gbase, voff) do { _Pragma("unroll") for (int _i = 0; _i < 2; ++_i) \
;         __builtin_amdgcn_global_load_lds((const unsigned*)((const char*)(gbase) + (voff)[_i]), (PG8_LAS unsigned*)(lds + (bufoff) + ldsw + _i * 8192), 16, 0, 0); } while (0)
; #define PG8_LDA(dst, b, h) do { _Pragma("unroll") for (int m = 0; m < 4; ++m) _Pragma("unroll") for (int k = 0; k < 2; ++k) dst[m][k] = *(const PG8_LAS bf16x8*)(lds + PG8_SA(b, h) + aoff + m * 2048 + k * 1024); } while (0)
; #define PG8_LDB(dst, b, h) do { _Pragma("unroll") for (int n = 0; n < 2; ++n) _Pragma("unroll") for (int k = 0; k < 2; ++k) dst[n][k] = *(const PG8_LAS bf16x8*)(lds + PG8_SB(b, h) + boff + n * 2048 + k * 1024); } while (0)
; #define PG8_MMA(ai, bj, At, Bt) do { __builtin_amdgcn_s_setprio(1); _Pragma("unroll") for (int m = 0; m < 4; ++m) _Pragma("unroll") for (int n = 0; n < 2; ++n) _Pragma("unroll") for (int k = 0; k < 2; ++k) \
;         acc[ai][bj][m][n] = __builtin_amdgcn_mfma_f32_16x16x32_bf16(Bt[n][k], At[m][k], acc[ai][bj][m][n], 0, 0, 0); __builtin_amdgcn_s_setprio(0); } while (0)
; #define PG8_WAIT_V(n) asm volatile("s_waitcnt vmcnt(" #n ")" ::: "memory")
; #define PG8_WAIT_L(n) asm volatile("s_waitcnt lgkmcnt(" #n ")" ::: "memory")
; #define PG8_BAR __builtin_amdgcn_s_barrier()
; #define PG8_SCHED __builtin_amdgcn_sched_barrier(0)
; template <class Epi, class Sched, bool ALIGN_EPI = false, bool SP2 = false>
; __device__ __forceinline__ void gemm_phase(PG8_LAS unsigned char* lds, const Gemm g, const Sched& S, const Epi& E) {
;     ...
;             PG8_LDB(B0, 1, 0); PG8_LDB(B1, 1, 1); PG8_SCHED; PG8_LDA(At, 1, 0); PG8_STAGE(PG8_SA(0, 1), a2 + hstep, voffA);
;             PG8_WAIT_V(8); PG8_WAIT_L(0); PG8_BAR; PG8_MMA(0, 0, At, B0); PG8_MMA(0, 1, At, B1); PG8_BAR; PG8_SCHED;
;             PG8_LDA(At, 1, 1); PG8_STAGE(PG8_SB(1, 0), b3, voffB); PG8_STAGE(PG8_SB(1, 1), b3 + hstep, voffB); PG8_STAGE(PG8_SA(1, 0), a3, voffA);
;             PG8_WAIT_V(8); PG8_WAIT_L(0); PG8_BAR; PG8_MMA(1, 0, At, B0); PG8_MMA(1, 1, At, B1); PG8_BAR; PG8_SCHED;
	v_mfma_f32_16x16x32_bf16 v[126:129], v[146:149], v[192:195], v[126:129]
	s_add_i32 m0, s39, 0x18000
	v_mfma_f32_16x16x32_bf16 v[118:121], v[154:157], v[192:195], v[118:121]
	global_load_lds_dwordx4 v134, s[46:47]
	v_mfma_f32_16x16x32_bf16 v[122:125], v[176:179], v[192:195], v[122:125]
	v_mfma_f32_16x16x32_bf16 v[114:117], v[184:187], v[192:195], v[114:117]
	s_add_i32 m0, s39, 0x1a000
	v_mfma_f32_16x16x32_bf16 v[126:129], v[150:153], v[196:199], v[126:129]
	global_load_lds_dwordx4 v130, s[46:47]
	v_mfma_f32_16x16x32_bf16 v[118:121], v[158:161], v[196:199], v[118:121]
	v_mfma_f32_16x16x32_bf16 v[122:125], v[180:183], v[196:199], v[122:125]
	s_add_i32 m0, s39, 0x1c000
	v_mfma_f32_16x16x32_bf16 v[114:117], v[188:191], v[196:199], v[114:117]
	global_load_lds_dwordx4 v134, s[68:69]
	v_mfma_f32_16x16x32_bf16 v[110:113], v[146:149], v[208:211], v[110:113]
	v_mfma_f32_16x16x32_bf16 v[102:105], v[154:157], v[208:211], v[102:105]
	s_add_i32 m0, s39, 0x1e000
	v_mfma_f32_16x16x32_bf16 v[106:109], v[176:179], v[208:211], v[106:109]
	global_load_lds_dwordx4 v130, s[68:69]
	v_mfma_f32_16x16x32_bf16 v[98:101], v[184:187], v[208:211], v[98:101]
	v_mfma_f32_16x16x32_bf16 v[110:113], v[150:153], v[212:215], v[110:113]
	s_add_i32 m0, s39, 0x8000
	v_mfma_f32_16x16x32_bf16 v[102:105], v[158:161], v[212:215], v[102:105]
	global_load_lds_dwordx4 v136, s[48:49]
	v_mfma_f32_16x16x32_bf16 v[106:109], v[180:183], v[212:215], v[106:109]
	v_mfma_f32_16x16x32_bf16 v[98:101], v[188:191], v[212:215], v[98:101]
	s_add_i32 m0, s39, 0xa000
	v_mfma_f32_16x16x32_bf16 v[94:97], v[146:149], v[216:219], v[94:97]
	global_load_lds_dwordx4 v132, s[48:49]
	v_mfma_f32_16x16x32_bf16 v[86:89], v[154:157], v[216:219], v[86:89]
	v_mfma_f32_16x16x32_bf16 v[90:93], v[176:179], v[216:219], v[90:93]
	v_mfma_f32_16x16x32_bf16 v[82:85], v[184:187], v[216:219], v[82:85]
	v_mfma_f32_16x16x32_bf16 v[94:97], v[150:153], v[220:223], v[94:97]
	v_mfma_f32_16x16x32_bf16 v[86:89], v[158:161], v[220:223], v[86:89]
	v_mfma_f32_16x16x32_bf16 v[90:93], v[180:183], v[220:223], v[90:93]
	v_mfma_f32_16x16x32_bf16 v[82:85], v[188:191], v[220:223], v[82:85]
	v_mfma_f32_16x16x32_bf16 v[76:79], v[146:149], v[224:227], v[76:79]
	v_mfma_f32_16x16x32_bf16 v[68:71], v[154:157], v[224:227], v[68:71]
	v_mfma_f32_16x16x32_bf16 v[72:75], v[176:179], v[224:227], v[72:75]
	v_mfma_f32_16x16x32_bf16 v[64:67], v[184:187], v[224:227], v[64:67]
	v_mfma_f32_16x16x32_bf16 v[76:79], v[150:153], v[228:231], v[76:79]
	v_mfma_f32_16x16x32_bf16 v[68:71], v[158:161], v[228:231], v[68:71]
	v_mfma_f32_16x16x32_bf16 v[72:75], v[180:183], v[228:231], v[72:75]
	v_mfma_f32_16x16x32_bf16 v[64:67], v[188:191], v[228:231], v[64:67]
	s_setprio 0
	s_barrier
	ds_read_b128 v[192:195], v144 offset:49152
	ds_read_b128 v[196:199], v144 offset:50176
	ds_read_b128 v[208:211], v144 offset:51200
	ds_read_b128 v[212:215], v144 offset:52224
	ds_read_b128 v[216:219], v144 offset:53248
	ds_read_b128 v[220:223], v144 offset:54272
	ds_read_b128 v[224:227], v144 offset:55296
	ds_read_b128 v[228:231], v144 offset:56320
	s_waitcnt vmcnt(8)
	s_waitcnt lgkmcnt(0)
	s_setprio 1
	s_barrier
	v_mfma_f32_16x16x32_bf16 v[60:63], v[146:149], v[192:195], v[60:63]
	s_add_i32 m0, s39, 0xc000
	v_mfma_f32_16x16x32_bf16 v[52:55], v[154:157], v[192:195], v[52:55]
	global_load_lds_dwordx4 v138, s[70:71]
	v_mfma_f32_16x16x32_bf16 v[56:59], v[176:179], v[192:195], v[56:59]
	v_mfma_f32_16x16x32_bf16 v[48:51], v[184:187], v[192:195], v[48:51]
	s_add_i32 m0, s39, 0xe000
	v_mfma_f32_16x16x32_bf16 v[60:63], v[150:153], v[196:199], v[60:63]
	global_load_lds_dwordx4 v140, s[70:71]
	v_mfma_f32_16x16x32_bf16 v[52:55], v[158:161], v[196:199], v[52:55]
	v_mfma_f32_16x16x32_bf16 v[56:59], v[180:183], v[196:199], v[56:59]
	v_mfma_f32_16x16x32_bf16 v[48:51], v[188:191], v[196:199], v[48:51]
	v_mfma_f32_16x16x32_bf16 v[44:47], v[146:149], v[208:211], v[44:47]
	v_mfma_f32_16x16x32_bf16 v[36:39], v[154:157], v[208:211], v[36:39]
	v_mfma_f32_16x16x32_bf16 v[40:43], v[176:179], v[208:211], v[40:43]
	v_mfma_f32_16x16x32_bf16 v[32:35], v[184:187], v[208:211], v[32:35]
	v_mfma_f32_16x16x32_bf16 v[44:47], v[150:153], v[212:215], v[44:47]
	v_mfma_f32_16x16x32_bf16 v[36:39], v[158:161], v[212:215], v[36:39]
	v_mfma_f32_16x16x32_bf16 v[40:43], v[180:183], v[212:215], v[40:43]
	v_mfma_f32_16x16x32_bf16 v[32:35], v[188:191], v[212:215], v[32:35]
	v_mfma_f32_16x16x32_bf16 v[28:31], v[146:149], v[216:219], v[28:31]
	v_mfma_f32_16x16x32_bf16 v[20:23], v[154:157], v[216:219], v[20:23]
	v_mfma_f32_16x16x32_bf16 v[24:27], v[176:179], v[216:219], v[24:27]
	v_mfma_f32_16x16x32_bf16 v[16:19], v[184:187], v[216:219], v[16:19]
	v_mfma_f32_16x16x32_bf16 v[28:31], v[150:153], v[220:223], v[28:31]
	v_mfma_f32_16x16x32_bf16 v[20:23], v[158:161], v[220:223], v[20:23]
	v_mfma_f32_16x16x32_bf16 v[24:27], v[180:183], v[220:223], v[24:27]
	v_mfma_f32_16x16x32_bf16 v[16:19], v[188:191], v[220:223], v[16:19]
	v_mfma_f32_16x16x32_bf16 v[12:15], v[146:149], v[224:227], v[12:15]
	v_mfma_f32_16x16x32_bf16 v[4:7], v[154:157], v[224:227], v[4:7]
	v_mfma_f32_16x16x32_bf16 v[8:11], v[176:179], v[224:227], v[8:11]
	v_mfma_f32_16x16x32_bf16 v[0:3], v[184:187], v[224:227], v[0:3]
	v_mfma_f32_16x16x32_bf16 v[12:15], v[150:153], v[228:231], v[12:15]
	v_mfma_f32_16x16x32_bf16 v[4:7], v[158:161], v[228:231], v[4:7]
	v_mfma_f32_16x16x32_bf16 v[8:11], v[180:183], v[228:231], v[8:11]
	v_mfma_f32_16x16x32_bf16 v[0:3], v[188:191], v[228:231], v[0:3]
	s_waitcnt vmcnt(8)
	s_setprio 0
	s_barrier
	s_add_i32 s66, s66, 2
	s_add_u32 s44, s44, 0x100
	s_addc_u32 s45, s45, 0
	s_add_u32 s64, s64, 0x100
	s_addc_u32 s65, s65, 0
	s_cmp_gt_u32 s66, 13
	s_cbranch_scc0 .Lffn_kB
